# k18: k17 + grid barrier between S5 chunk-state GEMM and carry chain removed (chunk-state units re-mapped block-local; sample GLU block moved behind the next grid barrier)
# baseline (speedup 1.0000x reference)
; #define PG8_STAGE(bufoff, gbase, voff) do { _Pragma("unroll") for (int _i = 0; _i < 2; ++_i) \
;         __builtin_amdgcn_global_load_lds((const unsigned*)((const char*)(gbase) + (voff)[_i]), (LAS unsigned*)(lds + (bufoff) + ldsw + _i * 8192), 16, 0, 0); } while (0)
; #define PG8_WAIT_V(n) asm volatile("s_waitcnt vmcnt(" #n ")" ::: "memory")
; #define PG8_BAR __builtin_amdgcn_s_barrier()
; #define SB WSP(float, WS_SB)
; template <class Epi, class Sched>
; __device__ __forceinline__ void gemm_phase(LAS unsigned char* lds, const Gemm g, const Sched& S, const Epi& E) {
;     ...
;     for (int i = 0; i < 2; ++i) { int R, C; stage_rc(tid * 16 + i * 8192, R, C); const int Rb = Epi::PERM ? ((R & ~31) + perm32(R & 31)) : R;
;         voffA[i] = (unsigned)R * g.lda + (g.aplane ? (unsigned)(C >> 4) * g.aplane + (unsigned)((C & 15) * 2) : (unsigned)(C * 2)); voffB[i] = (unsigned)Rb * g.ldb + (unsigned)(C * 2); }
;     const size_t kstepA = g.kstepA, kstepB = g.kstepB;
;     const size_t hstepA = (size_t)HALF * g.lda, hstepB = (size_t)HALF * g.ldb;
;     const unsigned ldsw = (unsigned)wid * 1024u;
;     const int aoff = lds_byte(wr * 64 + fr, fq * 8), boff = lds_byte(wc * 32 + fr, fq * 8);
;     ...
;     Unit cur, nxt; int ui = 0;
;     if (!S.next(0, cur)) return;
;     f32x4 acc[2][2][4][2];
; #pragma unroll
;     for (int a = 0; a < 2; ++a)
; #pragma unroll
;         for (int b = 0; b < 2; ++b)
; #pragma unroll
;             for (int m = 0; m < 4; ++m)
; #pragma unroll
;                 for (int n = 0; n < 2; ++n) acc[a][b][m][n] = (f32x4){0.f, 0.f, 0.f, 0.f};
;     bf16x8 At[4][2], B0[2][2], B1[2][2];
;     const char* cA = cur.a; const char* cB = cur.b;
;     PG8_WAIT_V(0);
;     PG8_STAGE(PG8_SB(0, 0), cB, voffB); PG8_STAGE(PG8_SB(0, 1), cB + hstepB, voffB); PG8_STAGE(PG8_SA(0, 0), cA, voffA); PG8_STAGE(PG8_SA(0, 1), cA + hstepA, voffA);
;     if (wr == 1) PG8_BAR;
;     PG8_WAIT_V(2); PG8_BAR;
;     PG8_STAGE(PG8_SB(1, 0), cB + kstepB, voffB); PG8_STAGE(PG8_SA(1, 0), cA + kstepA, voffA); PG8_STAGE(PG8_SB(1, 1), cB + hstepB + kstepB, voffB);
;     PG8_WAIT_V(6); PG8_BAR;
; __global__ void __launch_bounds__(NTHR, 2) hymba_fwd(Params P) {
;     ...
;     {
;         pg8::Gemm g{UXR * 32, 256 * 2, 128, 128, 4, 0}; pg8::S5Order S{G, blk, (const char*)UX, (const char*)W1, (size_t)256 * 256 * 2};
;         EpiS E{SB};
;         pg8::gemm_phase<EpiS, pg8::S5Order>(lds, g, S, E);
;     }
.LBB0_602:
	s_or_b64 exec, exec, s[0:1]
	s_cmpk_lt_i32 s2, 0x200
	s_cselect_b64 s[6:7], -1, 0
	s_lshr_b32 s0, s33, 28
	s_add_i32 s0, s2, s0
	s_and_b32 s16, s2, 31
	s_and_b32 s0, s0, -16
	s_bfe_u32 s88, s2, 0x30005
	s_lshl_b32 s88, s88, 1
	s_mul_i32 s4, s88, 0x30000
	s_ashr_i32 s17, s16, 31
	s_mul_i32 s1, s16, 0x306000
	s_ashr_i32 s5, s4, 31
	s_mul_hi_i32 s0, s16, 0x306000
	s_add_u32 s1, s22, s1
	s_addc_u32 s0, s23, s0
	s_add_u32 s30, s1, s4
	v_mov_b32_e32 v8, v208
	v_writelane_b32 v255, s6, 20
	s_waitcnt lgkmcnt(0)
	s_barrier
	s_addc_u32 s31, s0, s5
	s_barrier
	v_writelane_b32 v255, s7, 21
	v_readfirstlane_b32 s4, v8
	s_and_b64 vcc, exec, s[6:7]
	s_cbranch_vccz .LBB0_616
	v_lshlrev_b32_e32 v1, 4, v8
	v_add_u32_e32 v0, 0x2000, v1
	v_ashrrev_i32_e32 v2, 31, v0
	v_lshrrev_b32_e32 v2, 22, v2
	v_add_u32_e32 v2, v0, v2
	v_ashrrev_i32_e32 v2, 10, v2
	v_mul_i32_i24_e32 v3, 0x400, v2
	v_sub_u32_e32 v0, v0, v3
	v_lshrrev_b32_e32 v3, 4, v0
	v_bitop3_b32 v0, v3, v0, 32 bitop3:0x6c
	v_ashrrev_i32_e32 v3, 31, v0
	v_lshrrev_b32_e32 v3, 26, v3
	v_add_u32_e32 v3, v0, v3
	v_lshlrev_b32_e32 v5, 3, v2
	v_ashrrev_i32_e32 v4, 6, v3
	v_and_b32_e32 v5, -16, v5
	v_and_b32_e32 v3, 0xc0, v3
	s_lshl_b64 s[0:1], s[16:17], 17
	v_readlane_b32 s5, v255, 14
	v_add_u32_e32 v5, v4, v5
	v_sub_u32_e32 v0, v0, v3
	v_mov_b32_e32 v3, 1
	s_add_u32 s70, s5, s0
	v_and_b32_e32 v4, 3, v4
	s_mov_b32 s5, 0x7fffe0
	v_lshrrev_b32_e32 v6, 2, v5
	v_lshlrev_b32_e32 v7, 1, v5
	v_lshlrev_b32_e32 v2, 5, v2
	v_ashrrev_i16_sdwa v0, v3, sext(v0) dst_sel:DWORD dst_unused:UNUSED_PAD src0_sel:DWORD src1_sel:BYTE_0
	v_and_or_b32 v4, v5, s5, v4
	v_and_b32_e32 v6, 4, v6
	v_and_b32_e32 v7, 24, v7
	v_and_b32_e32 v2, 32, v2
	v_bfe_i32 v0, v0, 0, 16
	v_or3_b32 v4, v4, v6, v7
	v_add_lshl_u32 v0, v2, v0, 1
	s_movk_i32 s12, 0x300
	v_lshl_add_u32 v64, v4, 9, v0
	v_mad_u64_u32 v[66:67], s[8:9], v5, s12, v[0:1]
	v_bfe_i32 v0, v8, 27, 1
	v_lshrrev_b32_e32 v0, 22, v0
	v_add_u32_e32 v0, v1, v0
	v_and_b32_e32 v0, 0xfffffc00, v0
	v_sub_u32_e32 v0, v1, v0
	v_lshrrev_b32_e32 v1, 4, v0
	v_ashrrev_i32_e32 v4, 31, v8
	v_bitop3_b32 v0, v1, v0, 32 bitop3:0x6c
	v_lshrrev_b32_e32 v4, 26, v4
	v_ashrrev_i32_e32 v1, 31, v0
	v_add_u32_e32 v4, v8, v4
	v_readlane_b32 s0, v255, 15
	v_lshrrev_b32_e32 v1, 26, v1
	v_ashrrev_i32_e32 v4, 6, v4
	s_addc_u32 s71, s0, s1
	s_ashr_i32 s10, s4, 6
	v_add_u32_e32 v1, v0, v1
	v_lshlrev_b32_e32 v5, 3, v4
	s_ashr_i32 s11, s4, 8
	s_lshl_b32 s28, s10, 10
	v_ashrrev_i32_e32 v2, 6, v1
	v_and_b32_e32 v5, -16, v5
	v_and_b32_e32 v1, 0xc0, v1
	s_add_u32 s0, s30, 0x18000
	v_add_u32_e32 v5, v2, v5
	v_sub_u32_e32 v0, v0, v1
	s_addc_u32 s1, s31, 0
	v_and_b32_e32 v2, 3, v2
	v_lshrrev_b32_e32 v6, 2, v5
	v_lshlrev_b32_e32 v7, 1, v5
	v_lshlrev_b32_e32 v4, 5, v4
	v_ashrrev_i16_sdwa v0, v3, sext(v0) dst_sel:DWORD dst_unused:UNUSED_PAD src0_sel:DWORD src1_sel:BYTE_0
	s_add_u32 s6, s70, 0x10000
	v_and_or_b32 v2, v5, s5, v2
	v_and_b32_e32 v6, 4, v6
	v_and_b32_e32 v7, 24, v7
	v_and_b32_e32 v4, 32, v4
	v_bfe_i32 v0, v0, 0, 16
	s_addc_u32 s7, s71, 0
	v_or3_b32 v2, v2, v6, v7
	v_add_lshl_u32 v0, v4, v0, 1
	s_add_i32 s17, s28, 0
	v_lshl_add_u32 v68, v2, 9, v0
	s_waitcnt vmcnt(0)
	s_add_i32 m0, s17, 0x10000
	s_add_i32 s20, s17, 0x14000
	global_load_lds_dwordx4 v68, s[70:71]
	s_add_i32 m0, s17, 0x12000
	s_add_i32 s21, s17, 0x16000
	global_load_lds_dwordx4 v64, s[70:71]
	s_mov_b32 m0, s20
	v_mad_u64_u32 v[70:71], s[8:9], v5, s12, v[0:1]
	global_load_lds_dwordx4 v68, s[6:7]
	s_mov_b32 m0, s21
	s_add_i32 s34, s17, 0x2000
	global_load_lds_dwordx4 v64, s[6:7]
	s_mov_b32 m0, s17
	s_add_i32 s35, s17, 0x4000
	global_load_lds_dwordx4 v70, s[30:31]
	s_mov_b32 m0, s34
	s_add_i32 s44, s17, 0x6000
	global_load_lds_dwordx4 v66, s[30:31]
	s_mov_b32 m0, s35
	v_mov_b32_e32 v73, 0
	global_load_lds_dwordx4 v70, s[0:1]
	s_mov_b32 m0, s44
	v_mov_b32_e32 v69, v73
	global_load_lds_dwordx4 v66, s[0:1]
	v_mov_b32_e32 v65, v73
	v_mov_b32_e32 v71, v73
	v_mov_b32_e32 v67, v73
	s_cmp_eq_u32 s11, 1
	s_mov_b64 s[14:15], s[96:97]
	s_mov_b32 s5, 0
	v_lshl_add_u64 v[6:7], s[70:71], 0, v[68:69]
	v_lshl_add_u64 v[4:5], s[70:71], 0, v[64:65]
	v_lshl_add_u64 v[0:1], s[30:31], 0, v[70:71]
	s_cselect_b64 s[6:7], -1, 0
	s_cmp_lg_u32 s11, 1
	v_lshl_add_u64 v[2:3], s[30:31], 0, v[66:67]
	s_cbranch_scc1 .LBB0_605
	s_barrier

;     __device__ bool next(int i, Unit& u) const {
;         const int L = i * G + c; if (L >= NG * (NCH / BM)) return false;
;         u.g = L / (NCH / BM); u.pm = L % (NCH / BM); u.pn = 0;
;         u.a = A + ((size_t)u.g * UXROWS + (size_t)u.pm * BM) * (UXR * 32); u.b = B + (size_t)u.g * wbytes; return true;
;     }
.LBB0_608:
	s_cmpk_lt_i32 s75, 0x200
	s_cselect_b64 s[62:63], -1, 0
	s_cmpk_gt_i32 s75, 0x1ff
	s_cbranch_scc1 .LBB0_610
	s_and_b32 s28, s75, 31
	s_bfe_u32 s29, s75, 0x30005
	s_lshl_b32 s29, s29, 1
	s_lshr_b32 s97, s75, 8
	s_add_i32 s97, s97, s29
	s_mul_i32 s60, s97, 0x30000
	s_ashr_i32 s29, s28, 31
	s_mul_i32 s59, s28, 0x306000
	s_ashr_i32 s61, s60, 31
	s_mul_hi_i32 s58, s28, 0x306000
	s_add_u32 s59, s22, s59
	s_addc_u32 vcc_lo, s23, s58
	s_add_u32 s58, s59, s60
	s_addc_u32 s59, vcc_lo, s61
	s_lshl_b64 s[60:61], s[28:29], 17
	v_readlane_b32 s29, v255, 14
	s_add_u32 s60, s29, s60
	v_readlane_b32 s29, v255, 15
	s_addc_u32 s61, s29, s61

; #define LAS __attribute__((address_space(3)))
; #define TIDS() const int tid = fresh_tid(), lane = tid & 63, wave = __builtin_amdgcn_readfirstlane(tid >> 6); (void)lane; (void)wave
; #define SB WSP(float, WS_SB)
; __device__ __forceinline__ void xcd_barrier(const XcdBarrier& b) {
;     asm volatile("s_waitcnt vmcnt(0)" ::: "memory");
;     __syncthreads();
;     if (threadIdx.x == 0) {
;         unsigned* bar = b.bar;
;         __builtin_amdgcn_s_waitcnt(0);
;         unsigned nloc = b.st[0], nx = b.st[1];
;         if (nloc == 0u) { xcd_barrier_complete(bar, b.x, nloc, nx); b.st[0] = nloc; b.st[1] = nx; }
; __global__ void __launch_bounds__(NTHR, 2) hymba_fwd(Params P) {
;     ...
;     for (int repc = 0; repc < REP_CH; ++repc) {
;     for (int it = blk; it < NB * NG; it += G) {
;         TIDS();
;         const int b = it >> 5, g = it & 31, n = lane, w = wave;
;         LAS f32x2* EE = (LAS f32x2*)lds;
;         const f32x2 a16 = A16[g * 64 + n];
;         const float* sp = SB + ((size_t)g * NCH + b * 512 + w * 64) * 128;
.LBB0_633:
	s_waitcnt vmcnt(0)
	s_barrier
	s_mov_b64 s[6:7], exec
	v_readlane_b32 s8, v255, 4
	v_readlane_b32 s9, v255, 5
	v_readlane_b32 s70, v255, 8
	s_and_b64 s[8:9], s[6:7], s[8:9]
	v_readlane_b32 s71, v255, 9
.LBB0_685:
	s_or_b64 exec, exec, s[6:7]
	s_waitcnt lgkmcnt(0)
	s_barrier
.LBB0_695:
	s_and_b64 vcc, exec, s[0:1]
	s_cbranch_vccnz .LBB0_713
	s_lshl_b32 s17, s2, 4
	s_lshl_b32 s20, s94, 4
	v_mov_b32_e32 v1, 0
	s_mov_b32 s21, 0x27300000
	s_mov_b32 s28, 0x27301000
	s_mov_b32 s29, 0x27302000
	s_mov_b32 s34, 0x27303000
	s_mov_b64 s[6:7], 0x4000
	s_movk_i32 s35, 0x7fff
	s_mov_b32 s44, 0xa001000
	s_mov_b32 s45, 0xa002000
	s_mov_b32 s46, 0xa003000
	s_mov_b32 s47, 0xa004000
	s_mov_b32 s48, 0xa005000
	s_mov_b64 s[8:9], 0x6000
	s_mov_b32 s49, s2
	s_mov_b32 s50, s2
	s_branch .LBB0_698

; #define LAS __attribute__((address_space(3)))
; __global__ void __launch_bounds__(NTHR, 2) hymba_fwd(Params P) {
;     ...
;     for (int it = blk; it < 128; it += G) {
;         const int mb = it & 15, ns = it >> 4;
;         LAS float* Cs = (LAS float*)lds; constexpr int ldc = 68;
;         __syncthreads();
;         skinny32(Cs, YSS + (size_t)(32 * mb) * SW, SW, WGLU, SW, 64, SW, [&](int ct) { return 64 * ns + 16 * ct; });
.LBB0_961:
	s_or_b64 exec, exec, s[0:1]
	v_readlane_b32 s6, v255, 20
	v_mov_b32_e32 v4, v208
	v_readlane_b32 s7, v255, 21
	s_waitcnt lgkmcnt(0)
	s_barrier
	s_cmpk_gt_i32 s2, 0x7f
	s_cbranch_scc1 .Lmy_glu_skip
	s_add_u32 s4, s92, 0x2f500000
	s_addc_u32 s5, s93, 0
	v_mov_b32_e32 v161, 0
	s_mov_b64 s[6:7], 0x4080
	s_mov_b64 s[8:9], 0x40c0
	s_mov_b64 s[10:11], 0x4100
	s_mov_b64 s[12:13], 0x4140
	s_mov_b64 s[28:29], 0x4180
	s_mov_b64 s[34:35], 0x41c0
	s_movk_i32 s17, 0x100
	s_mov_b64 s[44:45], 0x80
	s_mov_b64 s[46:47], 0xc0
	s_mov_b64 s[48:49], 0x140
	s_mov_b64 s[58:59], 0x180
	s_mov_b64 s[60:61], 0x1c0
	s_brev_b32 s20, 63
	s_mov_b32 s21, s2
	s_branch .LBB0_688

; #define PG8_STAGE(bufoff, gbase, voff) do { _Pragma("unroll") for (int _i = 0; _i < 2; ++_i) \
;         __builtin_amdgcn_global_load_lds((const unsigned*)((const char*)(gbase) + (voff)[_i]), (LAS unsigned*)(lds + (bufoff) + ldsw + _i * 8192), 16, 0, 0); } while (0)
; #define PG8_WAIT_V(n) asm volatile("s_waitcnt vmcnt(" #n ")" ::: "memory")
; template <class Epi, class Sched>
; __device__ __forceinline__ void gemm_phase(LAS unsigned char* lds, const Gemm g, const Sched& S, const Epi& E) {
;     ...
;     for (int i = 0; i < 2; ++i) { int R, C; stage_rc(tid * 16 + i * 8192, R, C); const int Rb = Epi::PERM ? ((R & ~31) + perm32(R & 31)) : R;
;         voffA[i] = (unsigned)R * g.lda + (g.aplane ? (unsigned)(C >> 4) * g.aplane + (unsigned)((C & 15) * 2) : (unsigned)(C * 2)); voffB[i] = (unsigned)Rb * g.ldb + (unsigned)(C * 2); }
;     const size_t kstepA = g.kstepA, kstepB = g.kstepB;
;     const size_t hstepA = (size_t)HALF * g.lda, hstepB = (size_t)HALF * g.ldb;
;     const unsigned ldsw = (unsigned)wid * 1024u;
;     const int aoff = lds_byte(wr * 64 + fr, fq * 8), boff = lds_byte(wc * 32 + fr, fq * 8);
;     ...
;     Unit cur, nxt; int ui = 0;
;     if (!S.next(0, cur)) return;
;     f32x4 acc[2][2][4][2];
; #pragma unroll
;     for (int a = 0; a < 2; ++a)
; #pragma unroll
;         for (int b = 0; b < 2; ++b)
; #pragma unroll
;             for (int m = 0; m < 4; ++m)
; #pragma unroll
;                 for (int n = 0; n < 2; ++n) acc[a][b][m][n] = (f32x4){0.f, 0.f, 0.f, 0.f};
;     bf16x8 At[4][2], B0[2][2], B1[2][2];
;     const char* cA = cur.a; const char* cB = cur.b;
;     PG8_WAIT_V(0);
;     PG8_STAGE(PG8_SB(0, 0), cB, voffB); PG8_STAGE(PG8_SB(0, 1), cB + hstepB, voffB); PG8_STAGE(PG8_SA(0, 0), cA, voffA); PG8_STAGE(PG8_SA(0, 1), cA + hstepA, voffA);
;     if (wr == 1) PG8_BAR;
;     PG8_WAIT_V(2); PG8_BAR;
;     PG8_STAGE(PG8_SB(1, 0), cB + kstepB, voffB); PG8_STAGE(PG8_SA(1, 0), cA + kstepA, voffA); PG8_STAGE(PG8_SB(1, 1), cB + hstepB + kstepB, voffB);
;     PG8_WAIT_V(6); PG8_BAR;
; __global__ void __launch_bounds__(NTHR, 2) hymba_fwd(Params P) {
;     ...
;     for (int rep6 = 0; rep6 < REP_P6; ++rep6) {
;         pg8::Gemm g{32, SW * 2, (size_t)4 * PT * 32, 128, SW / 64, (unsigned)(PT * 32)}; pg8::StaticOrder S; S.init(PT, SW, G, blk, YS, WGLU, 32, SW * 2);
;         EpiGlu E{YS, ZS, P.b_glu, MX};
;         pg8::gemm_phase<EpiGlu, pg8::StaticOrder>(lds, g, S, E);
;     }
.Lmy_glu_end:
	s_add_u32 s4, s92, 0x2b400000
	s_addc_u32 s5, s93, 0
	v_readlane_b32 s6, v255, 20
	v_readlane_b32 s7, v255, 21
	v_mov_b32_e32 v4, v208
	s_nop 3
.Lmy_glu_skip:
	s_and_b64 vcc, exec, s[6:7]
	v_readfirstlane_b32 s1, v4
	s_cbranch_vccz .LBB0_981
	v_lshlrev_b32_e32 v0, 4, v4
	v_add_u32_e32 v1, 0x2000, v0
	v_ashrrev_i32_e32 v2, 31, v1
	v_lshrrev_b32_e32 v2, 22, v2
	v_add_u32_e32 v2, v1, v2
	v_ashrrev_i32_e32 v5, 10, v2
	v_mul_i32_i24_e32 v2, 0x400, v5
	v_sub_u32_e32 v1, v1, v2
	v_lshrrev_b32_e32 v2, 4, v1
	v_bitop3_b32 v1, v2, v1, 32 bitop3:0x6c
	v_ashrrev_i32_e32 v2, 31, v1
	v_lshrrev_b32_e32 v2, 26, v2
	v_add_u32_e32 v2, v1, v2
	v_lshlrev_b32_e32 v3, 3, v5
	v_ashrrev_i32_e32 v6, 6, v2
	v_and_b32_e32 v3, -16, v3
	v_add_u32_e32 v3, v6, v3
	v_and_b32_e32 v7, 3, v6
	s_mov_b32 s0, 0x3fffe0
	v_lshrrev_b32_e32 v8, 2, v3
	v_lshlrev_b32_e32 v9, 1, v3
	v_and_or_b32 v7, v3, s0, v7
	v_and_b32_e32 v8, 4, v8
	v_and_b32_e32 v9, 24, v9
	v_and_b32_e32 v2, 0xc0, v2
	v_or3_b32 v7, v7, v8, v9
	v_lshlrev_b32_e32 v8, 5, v5
	v_sub_u32_e32 v1, v1, v2
	v_mov_b32_e32 v2, 1
	v_and_b32_e32 v8, 32, v8
	v_ashrrev_i16_sdwa v1, v2, sext(v1) dst_sel:DWORD dst_unused:UNUSED_PAD src0_sel:DWORD src1_sel:BYTE_0
	v_add_u32_sdwa v1, v8, sext(v1) dst_sel:DWORD dst_unused:UNUSED_PAD src0_sel:DWORD src1_sel:WORD_0
	v_lshlrev_b32_e32 v8, 1, v1
	v_lshlrev_b32_e32 v1, 17, v1
	v_lshl_add_u32 v156, v7, 10, v8
	v_and_b32_e32 v7, 30, v8
	v_and_b32_e32 v8, 0xffe00000, v1
	v_bfe_i32 v1, v4, 27, 1
	v_lshrrev_b32_e32 v1, 22, v1
	v_add_u32_e32 v1, v0, v1
	v_and_b32_e32 v1, 0xfffffc00, v1
	v_lshl_or_b32 v3, v3, 5, v7
	v_sub_u32_e32 v0, v0, v1
	v_add_u32_e32 v158, v3, v8
	v_lshrrev_b32_e32 v1, 4, v0
	v_ashrrev_i32_e32 v3, 31, v4
	v_bitop3_b32 v0, v1, v0, 32 bitop3:0x6c
	v_lshrrev_b32_e32 v3, 26, v3
	v_ashrrev_i32_e32 v1, 31, v0
	v_add_u32_e32 v3, v4, v3
	v_lshrrev_b32_e32 v1, 26, v1
	v_ashrrev_i32_e32 v10, 6, v3
	v_add_u32_e32 v1, v0, v1
	v_lshlrev_b32_e32 v3, 3, v10
	s_ashr_i32 s8, s1, 6
	v_ashrrev_i32_e32 v9, 6, v1
	v_and_b32_e32 v3, -16, v3
	s_ashr_i32 s10, s1, 8
	s_lshl_b32 s20, s8, 10
	v_add_u32_e32 v3, v9, v3
	v_and_b32_e32 v11, 3, v9
	s_lshl_b32 s9, s64, 6
	v_and_or_b32 v11, v3, s0, v11
	s_mul_i32 s0, s64, 0x41
	s_and_b64 s[6:7], s[66:67], exec
	s_cselect_b32 s0, s0, s9
	v_readlane_b32 s6, v255, 22
	s_add_i32 s0, s0, s6
	s_ashr_i32 s6, s0, 31
	s_lshr_b32 s6, s6, 28
	s_add_i32 s6, s0, s6
	s_ashr_i32 s7, s6, 4
	s_and_b32 s6, s6, 0xfff0
	s_sub_i32 s6, s0, s6
	s_bfe_i32 s0, s6, 0x80000
	s_bfe_u32 s0, s0, 0x3000c
	s_add_i32 s9, s6, s0
	s_bfe_i32 s0, s9, 0x80000
	s_and_b32 s9, s9, 0xf8
	s_sub_i32 s6, s6, s9
	s_lshl_b32 s7, s7, 3
	s_sext_i32_i8 s6, s6
	s_add_i32 s24, s7, s6
	s_sext_i32_i16 s0, s0
	s_ashr_i32 s25, s24, 31
	v_lshrrev_b32_e32 v12, 2, v3
	v_lshlrev_b32_e32 v13, 1, v3
	s_lshr_b32 s0, s0, 3
	s_lshl_b64 s[6:7], s[24:25], 13
	v_and_b32_e32 v12, 4, v12
	v_and_b32_e32 v13, 24, v13
	v_and_b32_e32 v1, 0xc0, v1
	s_add_u32 s26, s4, s6
	v_or3_b32 v11, v11, v12, v13
	v_lshlrev_b32_e32 v12, 5, v10
	v_sub_u32_e32 v0, v0, v1
	s_addc_u32 s27, s5, s7
	s_bfe_i64 s[6:7], s[0:1], 0x100000
	v_and_b32_e32 v12, 32, v12
	v_ashrrev_i16_sdwa v0, v2, sext(v0) dst_sel:DWORD dst_unused:UNUSED_PAD src0_sel:DWORD src1_sel:BYTE_0
	s_lshl_b64 s[6:7], s[6:7], 18
	v_readlane_b32 s12, v255, 16
	v_add_u32_sdwa v0, v12, sext(v0) dst_sel:DWORD dst_unused:UNUSED_PAD src0_sel:DWORD src1_sel:WORD_0
	v_readlane_b32 s13, v255, 17
	s_add_u32 s28, s12, s6
	v_lshlrev_b32_e32 v1, 1, v0
	s_addc_u32 s29, s13, s7
	s_add_i32 s21, s20, 0
	v_lshl_add_u32 v160, v11, 10, v1
	s_waitcnt vmcnt(0)
	s_add_i32 m0, s21, 0x10000
	v_and_b32_e32 v11, 30, v1
	global_load_lds_dwordx4 v160, s[28:29]
	s_add_i32 m0, s21, 0x12000
	s_add_u32 s6, s28, 0x20000
	v_lshlrev_b32_e32 v0, 17, v0
	global_load_lds_dwordx4 v156, s[28:29]
	s_addc_u32 s7, s29, 0
	s_add_i32 m0, s21, 0x14000
	v_lshl_or_b32 v1, v3, 5, v11
	v_and_b32_e32 v12, 0xffe00000, v0
	global_load_lds_dwordx4 v160, s[6:7]
	s_add_i32 m0, s21, 0x16000
	s_add_i32 s25, s21, 0x2000
	v_add_u32_e32 v162, v1, v12
	global_load_lds_dwordx4 v156, s[6:7]
	s_mov_b32 m0, s21
	s_add_u32 s6, s26, 0x1000
	global_load_lds_dwordx4 v162, s[26:27]
	s_mov_b32 m0, s25
	s_addc_u32 s7, s27, 0
	s_add_i32 s42, s21, 0x4000
	global_load_lds_dwordx4 v158, s[26:27]
	s_mov_b32 m0, s42
	s_add_i32 s43, s21, 0x6000
	global_load_lds_dwordx4 v162, s[6:7]
	s_mov_b32 m0, s43
	v_mov_b32_e32 v161, 0
	global_load_lds_dwordx4 v158, s[6:7]
	v_mov_b32_e32 v157, v161
	s_cmp_eq_u32 s10, 1
	s_mov_b32 s44, 0
	v_lshl_add_u64 v[2:3], s[28:29], 0, v[160:161]
	v_lshl_add_u64 v[0:1], s[28:29], 0, v[156:157]
	v_mov_b32_e32 v163, v161
	s_cselect_b64 s[6:7], -1, 0
	s_cmp_lg_u32 s10, 1
	v_mov_b32_e32 v159, v161
	s_cbranch_scc1 .LBB0_964
	s_barrier
